# v029 + MoBA attention loop: first tile's K-fragment LDS reads issued at the loop top right after the barrier
# speedup vs baseline: 1.0199x; 1.0049x over previous
; #define LAS __attribute__((address_space(3)))
;     __device__ __forceinline__ bool skip(int t) const { const int nb = t >> 2; if (nb >= qb) return 64 * (t & 3) > wq0 + 31; return !__any((int)((sel >> nb) & 1u)); }
; template <bool HAS_POST, class MaskF>
; __device__ __forceinline__ void attn_run(LAS unsigned char* lds, const bf16* Kg, const bf16* Vg, int pitch, int t0, int t1,
;                                          const bf16x8 (&qr)[4], f32x16& o0, f32x16& o1, f32x16& o2, MaskF& mf, const int wv) {
;     ...
;     for (int ts = t0; ts < t1; ts += 2) {
;         const int cur = ((ts - t0) >> 1) & 1;
;         const bool more = (ts + 2 < t1), more2 = (ts + 3 < t1);
;         if (more) { kp += 2 * tstride; kreg0 = *(const v4u*)kp; vp += 2 * tstride; vreg0 = *(const v4u*)vp;
;             if (more2) { kreg1 = *(const v4u*)(kp + tstride); vreg1 = *(const v4u*)(vp + tstride); } }
; #pragma unroll
;         for (int j = 0; j < 2; ++j) {
;             const int t = ts + j;
;             if (t >= t1) break;
;             if (mf.skip(t)) continue;
;             f32x16 p0, p1; const f32x16 zc = {};
;             LAS unsigned char* Kb = lds + (cur * 2 + j) * KBUF + cx.kroff;
;             if (wv < 4) __builtin_amdgcn_s_setprio(1);
; #pragma unroll
;             for (int d0 = 0; d0 < 4; ++d0) {
;                 const bf16x8 a0 = *(const LAS bf16x8*)(Kb + d0 * 32), a1 = *(const LAS bf16x8*)(Kb + 32 * 144 + d0 * 32);
.LBB0_1166:
	s_add_i32 s1, s37, -1
	s_and_b32 s99, s1, 2
	s_mul_i32 s98, s99, 0x2400
	v_add_u32_e32 v124, s98, v165
	ds_read_b128 v[120:123], v124
	ds_read_b128 v[128:131], v124 offset:32
	ds_read_b128 v[176:179], v124 offset:4608
	ds_read_b128 v[132:135], v124 offset:4640
	ds_read_b128 v[136:139], v124 offset:64
	ds_read_b128 v[140:143], v124 offset:4672
	ds_read_b128 v[144:147], v124 offset:96
	ds_read_b128 v[148:151], v124 offset:4704
	s_add_i32 s58, s37, 1
	s_cmp_lt_u32 s58, s35
	s_cselect_b64 s[4:5], -1, 0
	s_cmp_le_u32 s1, s34
	s_cselect_b64 s[6:7], 0, exec
	s_cmp_ge_u32 s58, s35
	s_cbranch_scc1 .LBB0_1170
	s_mov_b64 s[8:9], 0x100000
	v_lshl_add_u64 v[154:155], v[154:155], 0, s[8:9]
	v_lshl_add_u64 v[156:157], v[156:157], 0, s[8:9]
	global_load_dwordx4 v[96:99], v[154:155], off
	global_load_dwordx4 v[100:103], v[156:157], off
	s_and_b64 vcc, exec, s[6:7]
	s_cbranch_vccnz .LBB0_1169
	s_mov_b64 s[8:9], 0x80000
	v_lshl_add_u64 v[174:175], v[154:155], 0, s[8:9]
	global_load_dwordx4 v[104:107], v[174:175], off
	v_lshl_add_u64 v[174:175], v[156:157], 0, s[8:9]
	global_load_dwordx4 v[108:111], v[174:175], off

; #define LAS __attribute__((address_space(3)))
; template <bool HAS_POST, class MaskF>
; __device__ __forceinline__ void attn_run(LAS unsigned char* lds, const bf16* Kg, const bf16* Vg, int pitch, int t0, int t1,
;                                          const bf16x8 (&qr)[4], f32x16& o0, f32x16& o1, f32x16& o2, MaskF& mf, const int wv) {
;     ...
;             LAS unsigned char* Kb = lds + (cur * 2 + j) * KBUF + cx.kroff;
;             if (wv < 4) __builtin_amdgcn_s_setprio(1);
; #pragma unroll
;             for (int d0 = 0; d0 < 4; ++d0) {
;                 const bf16x8 a0 = *(const LAS bf16x8*)(Kb + d0 * 32), a1 = *(const LAS bf16x8*)(Kb + 32 * 144 + d0 * 32);
;                 if (d0 == 0) { p0 = __builtin_amdgcn_mfma_f32_32x32x16_bf16(a0, qr[0], zc, 0, 0, 0); p1 = __builtin_amdgcn_mfma_f32_32x32x16_bf16(a1, qr[0], zc, 0, 0, 0); }
;                 else { p0 = __builtin_amdgcn_mfma_f32_32x32x16_bf16(a0, qr[d0], p0, 0, 0, 0); p1 = __builtin_amdgcn_mfma_f32_32x32x16_bf16(a1, qr[d0], p1, 0, 0, 0); }
;             }
;             if (wv < 4) __builtin_amdgcn_s_setprio(0);
.LBB0_1175:
	s_mul_i32 s1, s59, 0x2400
	s_and_b64 vcc, exec, s[8:9]
	s_waitcnt lgkmcnt(7)
	v_mfma_f32_32x32x16_bf16 v[64:79], v[120:123], v[80:83], 0
	s_waitcnt lgkmcnt(6)
	v_mfma_f32_32x32x16_bf16 v[64:79], v[128:131], v[84:87], v[64:79]
	s_waitcnt lgkmcnt(5)
	v_mfma_f32_32x32x16_bf16 v[48:63], v[176:179], v[80:83], 0
	s_waitcnt lgkmcnt(4)
	v_mfma_f32_32x32x16_bf16 v[48:63], v[132:135], v[84:87], v[48:63]
	s_waitcnt lgkmcnt(3)
	v_mfma_f32_32x32x16_bf16 v[64:79], v[136:139], v[88:91], v[64:79]
	s_waitcnt lgkmcnt(2)
	v_mfma_f32_32x32x16_bf16 v[48:63], v[140:143], v[88:91], v[48:63]
	s_waitcnt lgkmcnt(1)
	v_mfma_f32_32x32x16_bf16 v[64:79], v[144:147], v[92:95], v[64:79]
	s_waitcnt lgkmcnt(0)
	v_mfma_f32_32x32x16_bf16 v[48:63], v[148:151], v[92:95], v[48:63]
	s_cbranch_vccnz .LBB0_1177
	s_setprio 0
